# GLA chunk loop: row-sum reductions via 16 parallel DPP butterflies, wide RS reads; diff-attention loop: K and V LDS fragment reads hoisted with counted waits
# speedup vs baseline: 1.1179x; 1.1179x over previous
; #define MFMA16(a, b, c) __builtin_amdgcn_mfma_f32_16x16x32_bf16((a), (b), (c), 0, 0, 0)
; template <int MODE>
; __device__ __forceinline__ void attn_item(const Params& p, unsigned char* sm, int h, int tok0, int nrows, int kvt0, int ntiles, int nkeys, int qpos0, const int TIDX) {
;     ...
;         const unsigned char* Kb = sm + (t & 1) * 35840; const unsigned char* Vb = Kb + 17408;
;         f32x4 s[4];
; #pragma unroll
;         for (int kb = 0; kb < 4; ++kb) {
;             f32x4 acc = (f32x4){0.f, 0.f, 0.f, 0.f};
; #pragma unroll
;             for (int ks = 0; ks < KS; ++ks) {
;                 const bf16x8 A = *(const bf16x8*)(Kb + (16 * kb + r16) * 272 + (doff + 32 * ks + 8 * g) * 2);
;                 acc = MFMA16(A, Qf[ks], acc);
;             }
;             s[kb] = acc;
;         }
;         float mx = -1e30f;
;         if ((MODE == 1 || (64 * t + 63 - qpos0 <= -128)) && 64 * (t + 1) <= nkeys) {
;             const float bfar = MODE == 0 ? BIAS[0] : 0.f;
; #pragma unroll
;             for (int kb = 0; kb < 4; ++kb)
; #pragma unroll
;                 for (int j = 0; j < 4; ++j) { const float v = s[kb][j] * SC + bfar; s[kb][j] = v; mx = fmaxf(mx, v); }
;     ...
;                 const u32x2 a0 = *(const u32x2*)(Vb + (16 * cb + r16) * 144 + (32 * k2 + 4 * g) * 2);
;                 const u32x2 a1 = *(const u32x2*)(Vb + (16 * cb + r16) * 144 + (32 * k2 + 16 + 4 * g) * 2);
;                 const bf16x8 A = __builtin_bit_cast(bf16x8, ((u32x4){a0.x, a0.y, a1.x, a1.y}));
.LBB0_97:
	s_bitcmp1_b32 s14, 0
	s_cselect_b32 s14, 0x8c00, 0
	s_add_i32 s24, s14, 0
	v_add3_u32 v62, s24, v107, v106
	v_add3_u32 v63, s24, v108, v106
	v_add3_u32 v64, s24, v109, v106
	v_add3_u32 v80, s24, v110, v106
	v_add3_u32 v212, s24, v74, v111
	ds_read_b128 v[120:123], v62
	ds_read_b128 v[124:127], v62 offset:64
	ds_read_b128 v[128:131], v63
	ds_read_b128 v[132:135], v63 offset:64
	ds_read_b128 v[136:139], v64
	ds_read_b128 v[140:143], v64 offset:64
	ds_read_b128 v[144:147], v80
	ds_read_b128 v[148:151], v80 offset:64
	v_add_u32_e32 v213, 0x4000, v212
	ds_read2_b64 v[152:155], v213 offset0:128 offset1:132
	ds_read2_b64 v[156:159], v213 offset0:136 offset1:140
	v_add_u32_e32 v213, 0x4800, v212
	ds_read2_b64 v[160:163], v213 offset0:160 offset1:164
	ds_read2_b64 v[164:167], v213 offset0:168 offset1:172
	v_add_u32_e32 v213, 0x5000, v212
	ds_read2_b64 v[204:207], v213 offset0:192 offset1:196
	ds_read2_b64 v[208:211], v213 offset0:200 offset1:204
	s_add_i32 s14, s19, s22
	s_sub_i32 s14, s14, 64
	s_cmpk_gt_i32 s14, 0xff41
	s_cselect_b64 s[14:15], -1, 0
	s_cmp_gt_i32 s22, s17
	s_cselect_b64 s[26:27], -1, 0
	s_or_b64 s[26:27], s[14:15], s[26:27]
	s_mov_b64 s[14:15], -1
	s_andn2_b64 vcc, exec, s[26:27]
	s_waitcnt lgkmcnt(12)
	v_mfma_f32_16x16x32_bf16 v[66:69], v[120:123], v[34:37], 0
	v_mfma_f32_16x16x32_bf16 v[66:69], v[124:127], v[38:41], v[66:69]
	s_waitcnt lgkmcnt(10)
	v_mfma_f32_16x16x32_bf16 v[70:73], v[128:131], v[34:37], 0
	v_mfma_f32_16x16x32_bf16 v[70:73], v[132:135], v[38:41], v[70:73]
	s_waitcnt lgkmcnt(8)
	v_mfma_f32_16x16x32_bf16 v[58:61], v[136:139], v[34:37], 0
	v_mfma_f32_16x16x32_bf16 v[58:61], v[140:143], v[38:41], v[58:61]
	s_waitcnt lgkmcnt(6)
	v_mfma_f32_16x16x32_bf16 v[62:65], v[144:147], v[34:37], 0
	v_mfma_f32_16x16x32_bf16 v[62:65], v[148:151], v[38:41], v[62:65]
	s_nop 1
	v_mul_f32_e32 v66, 0x3e38aa3b, v66
	v_mul_f32_e32 v67, 0x3e38aa3b, v67
	s_cbranch_vccz .LBB0_99
	s_add_i32 s14, 0, 0x11800
	v_mov_b32_e32 v80, s14
	ds_read_b32 v94, v80
	s_mov_b32 s26, 0x3e38aa3b
	s_mov_b32 s14, 0xf149f2ca
	s_waitcnt lgkmcnt(0)
	v_pk_add_f32 v[84:85], v[66:67], v[94:95] op_sel_hi:[1,0]
	v_pk_fma_f32 v[86:87], v[68:69], s[26:27], v[94:95] op_sel_hi:[1,0,0]
	v_max3_f32 v90, v84, s14, v85
	v_pk_fma_f32 v[80:81], v[70:71], s[26:27], v[94:95] op_sel_hi:[1,0,0]
	v_max3_f32 v90, v90, v86, v87
	v_pk_fma_f32 v[82:83], v[72:73], s[26:27], v[94:95] op_sel_hi:[1,0,0]
	v_max3_f32 v90, v90, v80, v81
	v_pk_fma_f32 v[88:89], v[58:59], s[26:27], v[94:95] op_sel_hi:[1,0,0]
	v_max3_f32 v90, v90, v82, v83
	v_max3_f32 v92, v90, v88, v89
	v_pk_fma_f32 v[90:91], v[60:61], s[26:27], v[94:95] op_sel_hi:[1,0,0]
	s_mov_b64 s[14:15], 0
	v_max3_f32 v95, v92, v90, v91
	v_pk_fma_f32 v[92:93], v[62:63], s[26:27], v[94:95] op_sel_hi:[1,0,0]
	s_nop 0
	v_max3_f32 v115, v95, v92, v93
	v_pk_fma_f32 v[94:95], v[64:65], s[26:27], v[94:95] op_sel_hi:[1,0,0]
	s_nop 0
	v_max3_f32 v115, v115, v94, v95

; __device__ __forceinline__ unsigned pk2(float lo, float hi) { unsigned r; asm("v_cvt_pk_bf16_f32 %0, %1, %2" : "=v"(r) : "v"(lo), "v"(hi)); return r; }
; #define BAR_LDS() do { asm volatile("s_waitcnt lgkmcnt(0)" ::: "memory"); __builtin_amdgcn_s_barrier(); asm volatile("" ::: "memory"); } while (0)
; #define MFMA16(a, b, c) __builtin_amdgcn_mfma_f32_16x16x32_bf16((a), (b), (c), 0, 0, 0)
; #define AT_STORE(buf) do { unsigned char* b_ = sm + (buf) * 35840; _Pragma("unroll") for (int k_ = 0; k_ < 2; ++k_) { const int id_ = tid + 512 * k_; \
;         *(u32x4*)(b_ + (id_ >> 4) * 272 + (id_ & 15) * 16) = pkk[k_]; *(u32x4*)(b_ + 17408 + (id_ >> 3) * 144 + (id_ & 7) * 16) = pvv[k_]; } } while (0)
; template <int MODE>
; __device__ __forceinline__ void attn_item(const Params& p, unsigned char* sm, int h, int tok0, int nrows, int kvt0, int ntiles, int nkeys, int qpos0, const int TIDX) {
;     ...
;         mx = fmaxf(mx, __shfl_xor(mx, 16)); mx = fmaxf(mx, __shfl_xor(mx, 32));
;         const float mnew = fmaxf(m_run, mx), alpha = __builtin_amdgcn_exp2f(m_run - mnew); m_run = mnew;
;         float psum = 0.f;
; #pragma unroll
;         for (int kb = 0; kb < 4; ++kb)
; #pragma unroll
;             for (int j = 0; j < 4; ++j) { const float pv_ = __builtin_amdgcn_exp2f(s[kb][j] - mnew); s[kb][j] = pv_; psum += pv_; }
;         l_run = l_run * alpha + psum;
; #pragma unroll
;         for (int cb = 0; cb < 8; ++cb) O[cb] = O[cb] * alpha;
;         bf16x8 Pf[2];
; #pragma unroll
;         for (int k2 = 0; k2 < 2; ++k2) { u32x4 tt; tt.x = pk2(s[2 * k2][0], s[2 * k2][1]); tt.y = pk2(s[2 * k2][2], s[2 * k2][3]); tt.z = pk2(s[2 * k2 + 1][0], s[2 * k2 + 1][1]); tt.w = pk2(s[2 * k2 + 1][2], s[2 * k2 + 1][3]);
;             Pf[k2] = __builtin_bit_cast(bf16x8, tt); }
; #pragma unroll
;         for (int cb = 0; cb < 8; ++cb)
; #pragma unroll
;             for (int k2 = 0; k2 < 2; ++k2) {
;                 const u32x2 a0 = *(const u32x2*)(Vb + (16 * cb + r16) * 144 + (32 * k2 + 4 * g) * 2);
;                 const u32x2 a1 = *(const u32x2*)(Vb + (16 * cb + r16) * 144 + (32 * k2 + 16 + 4 * g) * 2);
;                 const bf16x8 A = __builtin_bit_cast(bf16x8, ((u32x4){a0.x, a0.y, a1.x, a1.y}));
;                 O[cb] = MFMA16(A, Pf[k2], O[cb]);
;             }
;         if (t + 1 < ntiles) AT_STORE((t + 1) & 1);
;         BAR_LDS();
.LBB0_101:
	ds_bpermute_b32 v58, v186, v115
	v_max_f32_e32 v59, v115, v115
	s_andn2_b64 vcc, exec, s[12:13]
	s_waitcnt lgkmcnt(0)
	v_max_f32_e32 v58, v58, v58
	v_max_f32_e32 v58, v59, v58
	ds_bpermute_b32 v59, v187, v58
	s_waitcnt lgkmcnt(0)
	v_max3_f32 v67, v114, v58, v59
	v_sub_f32_e32 v58, v114, v67
	v_exp_f32_e32 v66, v58
	v_sub_f32_e32 v58, v84, v67
	v_exp_f32_e32 v68, v58
	v_sub_f32_e32 v58, v85, v67
	v_exp_f32_e32 v69, v58
	v_sub_f32_e32 v58, v86, v67
	v_exp_f32_e32 v70, v58
	v_sub_f32_e32 v58, v87, v67
	v_exp_f32_e32 v71, v58
	v_sub_f32_e32 v58, v80, v67
	v_exp_f32_e32 v72, v58
	v_sub_f32_e32 v58, v81, v67
	v_exp_f32_e32 v73, v58
	v_sub_f32_e32 v58, v82, v67
	v_exp_f32_e32 v80, v58
	v_sub_f32_e32 v58, v83, v67
	v_exp_f32_e32 v81, v58
	v_sub_f32_e32 v58, v88, v67
	v_exp_f32_e32 v82, v58
	v_sub_f32_e32 v58, v89, v67
	v_exp_f32_e32 v83, v58
	v_sub_f32_e32 v58, v90, v67
	v_exp_f32_e32 v84, v58
	v_sub_f32_e32 v58, v91, v67
	v_exp_f32_e32 v85, v58
	v_sub_f32_e32 v58, v92, v67
	v_exp_f32_e32 v86, v58
	v_sub_f32_e32 v58, v93, v67
	v_exp_f32_e32 v87, v58
	v_sub_f32_e32 v58, v94, v67
	v_exp_f32_e32 v88, v58
	v_sub_f32_e32 v58, v95, v67
	v_pk_mul_f32 v[32:33], v[32:33], v[66:67] op_sel_hi:[1,0]
	v_pk_mul_f32 v[30:31], v[30:31], v[66:67] op_sel_hi:[1,0]
	v_cvt_pk_bf16_f32 v62, v68, v69
	v_cvt_pk_bf16_f32 v63, v70, v71
	v_cvt_pk_bf16_f32 v64, v72, v73
	v_cvt_pk_bf16_f32 v65, v80, v81
	v_exp_f32_e32 v89, v58
	s_nop 0
	v_mfma_f32_16x16x32_bf16 v[30:33], v[152:155], v[62:65], v[30:33]
	v_add_u32_e32 v213, 0x5800, v212
	ds_read2_b64 v[152:155], v213 offset0:224 offset1:228
	v_pk_mul_f32 v[60:61], v[4:5], v[66:67] op_sel_hi:[1,0]
	v_pk_mul_f32 v[58:59], v[2:3], v[66:67] op_sel_hi:[1,0]
	v_cvt_pk_bf16_f32 v2, v82, v83
	v_cvt_pk_bf16_f32 v3, v84, v85
	v_cvt_pk_bf16_f32 v4, v86, v87
	v_cvt_pk_bf16_f32 v5, v88, v89
	v_pk_mul_f32 v[24:25], v[24:25], v[66:67] op_sel_hi:[1,0]
	s_nop 0
	v_mfma_f32_16x16x32_bf16 v[30:33], v[156:159], v[2:5], v[30:33]
	ds_read2_b64 v[156:159], v213 offset0:232 offset1:236
	v_pk_mul_f32 v[22:23], v[22:23], v[66:67] op_sel_hi:[1,0]
	v_pk_mul_f32 v[28:29], v[28:29], v[66:67] op_sel_hi:[1,0]
	v_pk_mul_f32 v[26:27], v[26:27], v[66:67] op_sel_hi:[1,0]
	v_mfma_f32_16x16x32_bf16 v[22:25], v[160:163], v[62:65], v[22:25]
	v_add_u32_e32 v213, 0x6800, v212
	ds_read2_b64 v[160:163], v213 offset1:4
	v_pk_mul_f32 v[16:17], v[16:17], v[66:67] op_sel_hi:[1,0]
	v_mfma_f32_16x16x32_bf16 v[22:25], v[164:167], v[2:5], v[22:25]
	ds_read2_b64 v[164:167], v213 offset0:8 offset1:12
	v_pk_mul_f32 v[14:15], v[14:15], v[66:67] op_sel_hi:[1,0]
	v_pk_mul_f32 v[20:21], v[20:21], v[66:67] op_sel_hi:[1,0]
	v_mfma_f32_16x16x32_bf16 v[26:29], v[204:207], v[62:65], v[26:29]
	v_add_u32_e32 v213, 0x7000, v212
	ds_read2_b64 v[204:207], v213 offset0:32 offset1:36
	v_pk_mul_f32 v[18:19], v[18:19], v[66:67] op_sel_hi:[1,0]
	v_mfma_f32_16x16x32_bf16 v[26:29], v[208:211], v[2:5], v[26:29]
	ds_read2_b64 v[208:211], v213 offset0:40 offset1:44
	v_pk_mul_f32 v[8:9], v[8:9], v[66:67] op_sel_hi:[1,0]
	v_pk_mul_f32 v[6:7], v[6:7], v[66:67] op_sel_hi:[1,0]
	s_waitcnt lgkmcnt(5)
	v_mfma_f32_16x16x32_bf16 v[14:17], v[152:155], v[62:65], v[14:17]
	v_add_u32_e32 v213, 0x7800, v212
	ds_read2_b64 v[152:155], v213 offset0:64 offset1:68
	v_pk_mul_f32 v[12:13], v[12:13], v[66:67] op_sel_hi:[1,0]
	s_waitcnt lgkmcnt(5)
	v_mfma_f32_16x16x32_bf16 v[14:17], v[156:159], v[2:5], v[14:17]
	ds_read2_b64 v[156:159], v213 offset0:72 offset1:76
	v_pk_mul_f32 v[10:11], v[10:11], v[66:67] op_sel_hi:[1,0]
	s_waitcnt lgkmcnt(5)
	v_mfma_f32_16x16x32_bf16 v[18:21], v[160:163], v[62:65], v[18:21]
	v_add_u32_e32 v213, 0x8000, v212
	ds_read2_b64 v[160:163], v213 offset0:96 offset1:100
	s_waitcnt lgkmcnt(5)
	v_mfma_f32_16x16x32_bf16 v[18:21], v[164:167], v[2:5], v[18:21]
	ds_read2_b64 v[164:167], v213 offset0:104 offset1:108
	s_waitcnt lgkmcnt(5)
	v_mfma_f32_16x16x32_bf16 v[6:9], v[204:207], v[62:65], v[6:9]
	s_waitcnt lgkmcnt(4)
	v_mfma_f32_16x16x32_bf16 v[6:9], v[208:211], v[2:5], v[6:9]
	s_waitcnt lgkmcnt(3)
	v_mfma_f32_16x16x32_bf16 v[10:13], v[152:155], v[62:65], v[10:13]
	s_waitcnt lgkmcnt(2)
	v_mfma_f32_16x16x32_bf16 v[10:13], v[156:159], v[2:5], v[10:13]
	s_waitcnt lgkmcnt(1)
	v_mfma_f32_16x16x32_bf16 v[58:61], v[160:163], v[62:65], v[58:61]
	s_waitcnt lgkmcnt(0)
	v_mfma_f32_16x16x32_bf16 v[2:5], v[164:167], v[2:5], v[58:61]
	s_cbranch_vccnz .LBB0_103
	s_bitcmp1_b32 s23, 0
	s_cselect_b32 s12, 0x8c00, 0
	s_add_i32 s12, s12, 0
	s_nop 0
	v_add_u32_e32 v58, s12, v98
	v_add_u32_e32 v59, v58, v100
	v_add_u32_e32 v60, s12, v99
	v_add_u32_e32 v61, v60, v101
	v_add_u32_e32 v58, v58, v102
	v_add_u32_e32 v60, v60, v103
	s_waitcnt vmcnt(3)
	ds_write_b128 v59, v[42:45]
	s_waitcnt vmcnt(2)
	ds_write_b128 v61, v[46:49] offset:17408
	s_waitcnt vmcnt(1)
	ds_write_b128 v58, v[50:53]
	s_waitcnt vmcnt(0)
	ds_write_b128 v60, v[54:57] offset:17408

; #define MFMA16(a, b, c) __builtin_amdgcn_mfma_f32_16x16x32_bf16((a), (b), (c), 0, 0, 0)
; __device__ __forceinline__ void gla_item(const Params& p, unsigned char* sm, int h, int job0, int jobstride, int nchunks, int tok0, int nvalid, const float* s_init, float* s_out, const int TIDX) {
;     ...
; #pragma unroll
;         for (int ip = 0; ip < 2; ++ip) {
;             bf16x8 Af[2][2];
; #pragma unroll
;             for (int q = 0; q < 2; ++q)
; #pragma unroll
;                 for (int ks = 0; ks < 2; ++ks) Af[q][ks] = *(const bf16x8*)(AMl + (16 * (2 * ip + q) + r16) * 144 + (32 * ks + 8 * g) * 2);
;             __builtin_amdgcn_sched_barrier(0);
; #pragma unroll
;             for (int q = 0; q < 2; ++q)
; #pragma unroll
;                 for (int ks = 0; ks < 2; ++ks) { o[2 * ip + q][0] = MFMA16(Af[q][ks], Vf[ks][0], o[2 * ip + q][0]); o[2 * ip + q][1] = MFMA16(Af[q][ks], Vf[ks][1], o[2 * ip + q][1]); }
;             __builtin_amdgcn_sched_barrier(0);
;         }
;         u32x4 grv[4];
; #pragma unroll
;         for (int k_ = 0; k_ < 4; ++k_) { const int id_ = tid + 512 * k_, row_ = id_ >> 5, seg_ = id_ & 31;
;             grv[k_] = *(const u32x4*)(GRg + (size_t)(t0 + (row_ < nvalid ? row_ : 0)) * 1024 + h * 256 + seg_ * 8); }
; #pragma unroll
;         for (int ib = 0; ib < 4; ++ib)
; #pragma unroll
;             for (int j = 0; j < 4; ++j) {
;                 float s = o[ib][0][j] * o[ib][0][j] + o[ib][1][j] * o[ib][1][j];
;                 s += __shfl_xor(s, 1); s += __shfl_xor(s, 2); s += __shfl_xor(s, 4); s += __shfl_xor(s, 8);
;                 if (r16 == 0) SSQ[w * 64 + 16 * ib + 4 * g + j] = s;
;             }
.LBB0_131:
	s_waitcnt lgkmcnt(0)
	s_barrier
	ds_read_b128 v[152:155], v230
	ds_read_b128 v[238:241], v230 offset:64
	ds_read_b128 v[242:245], v230 offset:2304
	ds_read_b128 v[246:249], v230 offset:2368
	s_waitcnt lgkmcnt(3)
	v_mfma_f32_16x16x32_bf16 v[144:147], v[152:155], v[128:131], v[144:147]
	v_mfma_f32_16x16x32_bf16 v[148:151], v[152:155], v[164:167], v[148:151]
	s_waitcnt lgkmcnt(1)
	v_mfma_f32_16x16x32_bf16 v[136:139], v[242:245], v[128:131], v[136:139]
	v_mfma_f32_16x16x32_bf16 v[140:143], v[242:245], v[164:167], v[140:143]
	v_mfma_f32_16x16x32_bf16 v[156:159], v[238:241], v[132:135], v[144:147]
	v_mfma_f32_16x16x32_bf16 v[152:155], v[238:241], v[160:163], v[148:151]
	s_waitcnt lgkmcnt(0)
	v_mfma_f32_16x16x32_bf16 v[148:151], v[246:249], v[132:135], v[136:139]
	v_mfma_f32_16x16x32_bf16 v[144:147], v[246:249], v[160:163], v[140:143]
	s_nop 1
	ds_read_b128 v[136:139], v230 offset:4608
	ds_read_b128 v[238:241], v230 offset:4672
	ds_read_b128 v[242:245], v230 offset:6912
	ds_read_b128 v[246:249], v230 offset:6976
	s_waitcnt lgkmcnt(3)
	v_mfma_f32_16x16x32_bf16 v[120:123], v[136:139], v[128:131], v[120:123]
	v_mfma_f32_16x16x32_bf16 v[124:127], v[136:139], v[164:167], v[124:127]
	s_waitcnt lgkmcnt(1)
	v_mfma_f32_16x16x32_bf16 v[112:115], v[242:245], v[128:131], v[112:115]
	v_mfma_f32_16x16x32_bf16 v[116:119], v[242:245], v[164:167], v[116:119]
	v_mfma_f32_16x16x32_bf16 v[140:143], v[238:241], v[132:135], v[120:123]
	v_mfma_f32_16x16x32_bf16 v[136:139], v[238:241], v[160:163], v[124:127]
	s_waitcnt lgkmcnt(0)
	v_mfma_f32_16x16x32_bf16 v[132:135], v[246:249], v[132:135], v[112:115]
	v_mfma_f32_16x16x32_bf16 v[128:131], v[246:249], v[160:163], v[116:119]
	s_nop 1
	v_add_u32_e32 v112, s81, v223
	v_add_u32_e32 v114, s81, v222
	v_ashrrev_i32_e32 v113, 31, v112
	v_ashrrev_i32_e32 v115, 31, v114
	v_lshlrev_b64 v[112:113], 11, v[112:113]
	v_lshlrev_b64 v[114:115], 11, v[114:115]
	v_lshl_add_u64 v[112:113], v[182:183], 0, v[112:113]
	v_lshl_add_u64 v[114:115], v[182:183], 0, v[114:115]
	global_load_dwordx4 v[124:127], v[112:113], off
	global_load_dwordx4 v[120:123], v[114:115], off
	v_add_u32_e32 v112, s81, v221
	v_add_u32_e32 v114, s81, v220
	v_ashrrev_i32_e32 v113, 31, v112
	v_ashrrev_i32_e32 v115, 31, v114
	v_lshlrev_b64 v[112:113], 11, v[112:113]
	v_lshlrev_b64 v[114:115], 11, v[114:115]
	v_lshl_add_u64 v[112:113], v[182:183], 0, v[112:113]
	v_lshl_add_u64 v[114:115], v[182:183], 0, v[114:115]
	global_load_dwordx4 v[116:119], v[112:113], off
	s_nop 0
	global_load_dwordx4 v[112:115], v[114:115], off
	v_mul_f32_e32 v238, v152, v152
	v_mul_f32_e32 v239, v153, v153
	v_mul_f32_e32 v240, v154, v154
	v_mul_f32_e32 v241, v155, v155
	v_mul_f32_e32 v242, v144, v144
	v_mul_f32_e32 v243, v145, v145
	v_mul_f32_e32 v244, v146, v146
	v_mul_f32_e32 v245, v147, v147
	v_mul_f32_e32 v246, v136, v136
	v_mul_f32_e32 v247, v137, v137
	v_mul_f32_e32 v248, v138, v138
	v_mul_f32_e32 v249, v139, v139
	v_mul_f32_e32 v250, v128, v128
	v_mul_f32_e32 v251, v129, v129
	v_mul_f32_e32 v252, v130, v130
	v_mul_f32_e32 v253, v131, v131
	v_fmac_f32_e32 v238, v156, v156
	v_fmac_f32_e32 v239, v157, v157
	v_fmac_f32_e32 v240, v158, v158
	v_fmac_f32_e32 v241, v159, v159
	v_fmac_f32_e32 v242, v148, v148
	v_fmac_f32_e32 v243, v149, v149
	v_fmac_f32_e32 v244, v150, v150
	v_fmac_f32_e32 v245, v151, v151
	v_fmac_f32_e32 v246, v140, v140
	v_fmac_f32_e32 v247, v141, v141
	v_fmac_f32_e32 v248, v142, v142
	v_fmac_f32_e32 v249, v143, v143
	v_fmac_f32_e32 v250, v132, v132
	v_fmac_f32_e32 v251, v133, v133
	v_fmac_f32_e32 v252, v134, v134
	v_fmac_f32_e32 v253, v135, v135
	v_add_f32_dpp v238, v238, v238 quad_perm:[1,0,3,2] row_mask:0xf bank_mask:0xf
	v_add_f32_dpp v239, v239, v239 quad_perm:[1,0,3,2] row_mask:0xf bank_mask:0xf
	v_add_f32_dpp v240, v240, v240 quad_perm:[1,0,3,2] row_mask:0xf bank_mask:0xf
	v_add_f32_dpp v241, v241, v241 quad_perm:[1,0,3,2] row_mask:0xf bank_mask:0xf
	v_add_f32_dpp v242, v242, v242 quad_perm:[1,0,3,2] row_mask:0xf bank_mask:0xf
	v_add_f32_dpp v243, v243, v243 quad_perm:[1,0,3,2] row_mask:0xf bank_mask:0xf
	v_add_f32_dpp v244, v244, v244 quad_perm:[1,0,3,2] row_mask:0xf bank_mask:0xf
	v_add_f32_dpp v245, v245, v245 quad_perm:[1,0,3,2] row_mask:0xf bank_mask:0xf
	v_add_f32_dpp v246, v246, v246 quad_perm:[1,0,3,2] row_mask:0xf bank_mask:0xf
	v_add_f32_dpp v247, v247, v247 quad_perm:[1,0,3,2] row_mask:0xf bank_mask:0xf
	v_add_f32_dpp v248, v248, v248 quad_perm:[1,0,3,2] row_mask:0xf bank_mask:0xf
	v_add_f32_dpp v249, v249, v249 quad_perm:[1,0,3,2] row_mask:0xf bank_mask:0xf
	v_add_f32_dpp v250, v250, v250 quad_perm:[1,0,3,2] row_mask:0xf bank_mask:0xf
	v_add_f32_dpp v251, v251, v251 quad_perm:[1,0,3,2] row_mask:0xf bank_mask:0xf
	v_add_f32_dpp v252, v252, v252 quad_perm:[1,0,3,2] row_mask:0xf bank_mask:0xf
	v_add_f32_dpp v253, v253, v253 quad_perm:[1,0,3,2] row_mask:0xf bank_mask:0xf
	v_add_f32_dpp v238, v238, v238 quad_perm:[2,3,0,1] row_mask:0xf bank_mask:0xf
	v_add_f32_dpp v239, v239, v239 quad_perm:[2,3,0,1] row_mask:0xf bank_mask:0xf
	v_add_f32_dpp v240, v240, v240 quad_perm:[2,3,0,1] row_mask:0xf bank_mask:0xf
	v_add_f32_dpp v241, v241, v241 quad_perm:[2,3,0,1] row_mask:0xf bank_mask:0xf
	v_add_f32_dpp v242, v242, v242 quad_perm:[2,3,0,1] row_mask:0xf bank_mask:0xf
	v_add_f32_dpp v243, v243, v243 quad_perm:[2,3,0,1] row_mask:0xf bank_mask:0xf
	v_add_f32_dpp v244, v244, v244 quad_perm:[2,3,0,1] row_mask:0xf bank_mask:0xf
	v_add_f32_dpp v245, v245, v245 quad_perm:[2,3,0,1] row_mask:0xf bank_mask:0xf
	v_add_f32_dpp v246, v246, v246 quad_perm:[2,3,0,1] row_mask:0xf bank_mask:0xf
	v_add_f32_dpp v247, v247, v247 quad_perm:[2,3,0,1] row_mask:0xf bank_mask:0xf
; #define BAR_LDS() do { asm volatile("s_waitcnt lgkmcnt(0)" ::: "memory"); __builtin_amdgcn_s_barrier(); asm volatile("" ::: "memory"); } while (0)
; __device__ __forceinline__ void gla_item(const Params& p, unsigned char* sm, int h, int job0, int jobstride, int nchunks, int tok0, int nvalid, const float* s_init, float* s_out, const int TIDX) {
;     ...
; #pragma unroll
;         for (int ib = 0; ib < 4; ++ib)
; #pragma unroll
;             for (int j = 0; j < 4; ++j) {
;                 float s = o[ib][0][j] * o[ib][0][j] + o[ib][1][j] * o[ib][1][j];
;                 s += __shfl_xor(s, 1); s += __shfl_xor(s, 2); s += __shfl_xor(s, 4); s += __shfl_xor(s, 8);
;                 if (r16 == 0) SSQ[w * 64 + 16 * ib + 4 * g + j] = s;
;             }
;         BAR_LDS();
;         if (tid < 64) { float t = 0.f;
; #pragma unroll
;             for (int ww = 0; ww < 8; ++ww) t += SSQ[ww * 64 + tid];
;             RSl[tid] = rsqrtf(t * (1.0f / 256) + EPS); }
	v_add_f32_dpp v248, v248, v248 quad_perm:[2,3,0,1] row_mask:0xf bank_mask:0xf
	v_add_f32_dpp v249, v249, v249 quad_perm:[2,3,0,1] row_mask:0xf bank_mask:0xf
	v_add_f32_dpp v250, v250, v250 quad_perm:[2,3,0,1] row_mask:0xf bank_mask:0xf
	v_add_f32_dpp v251, v251, v251 quad_perm:[2,3,0,1] row_mask:0xf bank_mask:0xf
	v_add_f32_dpp v252, v252, v252 quad_perm:[2,3,0,1] row_mask:0xf bank_mask:0xf
	v_add_f32_dpp v253, v253, v253 quad_perm:[2,3,0,1] row_mask:0xf bank_mask:0xf
	v_add_f32_dpp v238, v238, v238 row_half_mirror row_mask:0xf bank_mask:0xf
	v_add_f32_dpp v239, v239, v239 row_half_mirror row_mask:0xf bank_mask:0xf
	v_add_f32_dpp v240, v240, v240 row_half_mirror row_mask:0xf bank_mask:0xf
	v_add_f32_dpp v241, v241, v241 row_half_mirror row_mask:0xf bank_mask:0xf
	v_add_f32_dpp v242, v242, v242 row_half_mirror row_mask:0xf bank_mask:0xf
	v_add_f32_dpp v243, v243, v243 row_half_mirror row_mask:0xf bank_mask:0xf
	v_add_f32_dpp v244, v244, v244 row_half_mirror row_mask:0xf bank_mask:0xf
	v_add_f32_dpp v245, v245, v245 row_half_mirror row_mask:0xf bank_mask:0xf
	v_add_f32_dpp v246, v246, v246 row_half_mirror row_mask:0xf bank_mask:0xf
	v_add_f32_dpp v247, v247, v247 row_half_mirror row_mask:0xf bank_mask:0xf
	v_add_f32_dpp v248, v248, v248 row_half_mirror row_mask:0xf bank_mask:0xf
	v_add_f32_dpp v249, v249, v249 row_half_mirror row_mask:0xf bank_mask:0xf
	v_add_f32_dpp v250, v250, v250 row_half_mirror row_mask:0xf bank_mask:0xf
	v_add_f32_dpp v251, v251, v251 row_half_mirror row_mask:0xf bank_mask:0xf
	v_add_f32_dpp v252, v252, v252 row_half_mirror row_mask:0xf bank_mask:0xf
	v_add_f32_dpp v253, v253, v253 row_half_mirror row_mask:0xf bank_mask:0xf
	v_add_f32_dpp v238, v238, v238 row_mirror row_mask:0xf bank_mask:0xf
	v_add_f32_dpp v239, v239, v239 row_mirror row_mask:0xf bank_mask:0xf
	v_add_f32_dpp v240, v240, v240 row_mirror row_mask:0xf bank_mask:0xf
	v_add_f32_dpp v241, v241, v241 row_mirror row_mask:0xf bank_mask:0xf
	v_add_f32_dpp v242, v242, v242 row_mirror row_mask:0xf bank_mask:0xf
	v_add_f32_dpp v243, v243, v243 row_mirror row_mask:0xf bank_mask:0xf
	v_add_f32_dpp v244, v244, v244 row_mirror row_mask:0xf bank_mask:0xf
	v_add_f32_dpp v245, v245, v245 row_mirror row_mask:0xf bank_mask:0xf
	v_add_f32_dpp v246, v246, v246 row_mirror row_mask:0xf bank_mask:0xf
	v_add_f32_dpp v247, v247, v247 row_mirror row_mask:0xf bank_mask:0xf
	v_add_f32_dpp v248, v248, v248 row_mirror row_mask:0xf bank_mask:0xf
	v_add_f32_dpp v249, v249, v249 row_mirror row_mask:0xf bank_mask:0xf
	v_add_f32_dpp v250, v250, v250 row_mirror row_mask:0xf bank_mask:0xf
	v_add_f32_dpp v251, v251, v251 row_mirror row_mask:0xf bank_mask:0xf
	v_add_f32_dpp v252, v252, v252 row_mirror row_mask:0xf bank_mask:0xf
	v_add_f32_dpp v253, v253, v253 row_mirror row_mask:0xf bank_mask:0xf
	v_add_u32_e32 v160, s83, v209
	s_and_saveexec_b64 s[38:39], s[10:11]
	ds_write_b128 v160, v[238:241]
	ds_write_b128 v160, v[242:245] offset:64
	ds_write_b128 v160, v[246:249] offset:128
	ds_write_b128 v160, v[250:253] offset:192
	s_or_b64 exec, exec, s[38:39]
	s_waitcnt lgkmcnt(0)
	s_barrier
	s_and_saveexec_b64 s[38:39], s[8:9]
	s_cbranch_execz .LBB0_165
	ds_read2st64_b32 v[160:161], v211 offset1:1
	ds_read2st64_b32 v[162:163], v211 offset0:2 offset1:3
	ds_read2st64_b32 v[164:165], v211 offset0:4 offset1:5
	ds_read2st64_b32 v[166:167], v211 offset0:6 offset1:7
	s_waitcnt lgkmcnt(0)
	v_add_f32_e32 v160, 0, v160
	v_add_f32_e32 v160, v160, v161
	v_add_f32_e32 v160, v160, v162
	v_add_f32_e32 v160, v160, v163
	v_add_f32_e32 v160, v160, v164
	v_add_f32_e32 v160, v160, v165
	v_add_f32_e32 v160, v160, v166
	v_add_f32_e32 v160, v160, v167
	v_fmamk_f32 v160, v160, 0x3b800000, v168
	v_cmp_gt_f32_e32 vcc, s97, v160
	v_mul_f32_e32 v161, 0x4b800000, v160
	s_nop 0
	v_cndmask_b32_e32 v160, v160, v161, vcc
	v_rsq_f32_e32 v160, v160
	s_nop 0
	v_mul_f32_e32 v161, 0x45800000, v160
	v_cndmask_b32_e32 v160, v160, v161, vcc
	ds_write_b32 v212, v160
; __device__ __forceinline__ unsigned pk2(float lo, float hi) { unsigned r; asm("v_cvt_pk_bf16_f32 %0, %1, %2" : "=v"(r) : "v"(lo), "v"(hi)); return r; }
; __device__ __forceinline__ float bflo(unsigned u) { return __uint_as_float(u << 16); }
; __device__ __forceinline__ float bfhi(unsigned u) { return __uint_as_float(u & 0xffff0000u); }
; __device__ __forceinline__ float silu_f(float x) { return x * __builtin_amdgcn_rcpf(1.0f + __expf(-x)); }
; #define BAR_LDS() do { asm volatile("s_waitcnt lgkmcnt(0)" ::: "memory"); __builtin_amdgcn_s_barrier(); asm volatile("" ::: "memory"); } while (0)
; __device__ __forceinline__ void gla_item(const Params& p, unsigned char* sm, int h, int job0, int jobstride, int nchunks, int tok0, int nvalid, const float* s_init, float* s_out, const int TIDX) {
;     ...
; #pragma unroll
;         for (int ib = 0; ib < 4; ++ib)
; #pragma unroll
;             for (int j = 0; j < 4; ++j) {
;                 const int i = 16 * ib + 4 * g + j; const float rs = RSl[i];
;                 *(bf16_t*)(OTl + i * 528 + (32 * w + r16) * 2) = (bf16_t)(pk2(o[ib][0][j] * rs, 0.f) & 0xffffu);
;                 *(bf16_t*)(OTl + i * 528 + (32 * w + 16 + r16) * 2) = (bf16_t)(pk2(o[ib][1][j] * rs, 0.f) & 0xffffu);
;             }
;         BAR_LDS();
; #pragma unroll
;         for (int k_ = 0; k_ < 4; ++k_) { const int id_ = tid + 512 * k_, row_ = id_ >> 5, seg_ = id_ & 31;
;             if (row_ < nvalid) {
;                 const u32x4 ov = *(const u32x4*)(OTl + row_ * 528 + seg_ * 16);
;                 const f32x4 ga = *(const f32x4*)(GNl + seg_ * 8), gb = *(const f32x4*)(GNl + seg_ * 8 + 4);
;                 const u32x4 gr = grv[k_]; u32x4 wv;
;                 wv.x = pk2(bflo(ov.x) * ga[0] * silu_f(bflo(gr.x)), bfhi(ov.x) * ga[1] * silu_f(bfhi(gr.x)));
;                 wv.y = pk2(bflo(ov.y) * ga[2] * silu_f(bflo(gr.y)), bfhi(ov.y) * ga[3] * silu_f(bfhi(gr.y)));
;                 wv.z = pk2(bflo(ov.z) * gb[0] * silu_f(bflo(gr.z)), bfhi(ov.z) * gb[1] * silu_f(bfhi(gr.z)));
;                 wv.w = pk2(bflo(ov.w) * gb[2] * silu_f(bflo(gr.w)), bfhi(ov.w) * gb[3] * silu_f(bfhi(gr.w)));
;                 *(u32x4*)(CAT + (size_t)(t0 + row_) * DM + h * 256 + seg_ * 8) = wv;
.LBB0_165:
	s_or_b64 exec, exec, s[38:39]
	s_waitcnt lgkmcnt(0)
	s_barrier
	ds_read_b128 v[238:241], v214
	ds_read_b128 v[242:245], v214 offset:64
	ds_read_b128 v[246:249], v214 offset:128
	ds_read_b128 v[250:253], v214 offset:192
	s_waitcnt lgkmcnt(0)
	v_mul_f32_e32 v152, v152, v238
	v_mul_f32_e32 v156, v156, v238
	v_mul_f32_e32 v153, v153, v239
	v_mul_f32_e32 v157, v157, v239
	v_mul_f32_e32 v154, v154, v240
	v_mul_f32_e32 v158, v158, v240
	v_mul_f32_e32 v155, v155, v241
	v_mul_f32_e32 v159, v159, v241
	v_cvt_pk_bf16_f32 v152, v152, v1
	v_cvt_pk_bf16_f32 v156, v156, v1
	v_cvt_pk_bf16_f32 v153, v153, v1
	v_cvt_pk_bf16_f32 v157, v157, v1
	v_cvt_pk_bf16_f32 v154, v154, v1
	v_cvt_pk_bf16_f32 v158, v158, v1
	v_cvt_pk_bf16_f32 v155, v155, v1
	v_cvt_pk_bf16_f32 v159, v159, v1
	ds_write_b16 v231, v152 offset:32
	ds_write_b16 v231, v156
	ds_write_b16 v232, v153 offset:32
	ds_write_b16 v232, v157
	ds_write_b16 v232, v154 offset:560
	ds_write_b16 v232, v158 offset:528
	ds_write_b16 v232, v155 offset:1088
	ds_write_b16 v232, v159 offset:1056
	v_mul_f32_e32 v144, v144, v242
	v_mul_f32_e32 v148, v148, v242
	v_mul_f32_e32 v145, v145, v243
	v_mul_f32_e32 v149, v149, v243
	v_mul_f32_e32 v146, v146, v244
	v_mul_f32_e32 v150, v150, v244
	v_mul_f32_e32 v147, v147, v245
	v_mul_f32_e32 v151, v151, v245
	v_cvt_pk_bf16_f32 v144, v144, v1
	v_cvt_pk_bf16_f32 v148, v148, v1
	v_cvt_pk_bf16_f32 v145, v145, v1
	v_cvt_pk_bf16_f32 v149, v149, v1
	v_cvt_pk_bf16_f32 v146, v146, v1
	v_cvt_pk_bf16_f32 v150, v150, v1
	v_cvt_pk_bf16_f32 v147, v147, v1
	v_cvt_pk_bf16_f32 v151, v151, v1
	ds_write_b16 v232, v144 offset:7952
	ds_write_b16 v232, v148 offset:7920
	ds_write_b16 v232, v145 offset:8480
	ds_write_b16 v232, v149 offset:8448
	ds_write_b16 v232, v146 offset:9008
	ds_write_b16 v232, v150 offset:8976
	ds_write_b16 v232, v147 offset:9536
	ds_write_b16 v232, v151 offset:9504
	v_mul_f32_e32 v136, v136, v246
	v_mul_f32_e32 v140, v140, v246
	v_mul_f32_e32 v137, v137, v247
	v_mul_f32_e32 v141, v141, v247
	v_mul_f32_e32 v138, v138, v248
	v_mul_f32_e32 v142, v142, v248
	v_mul_f32_e32 v139, v139, v249
	v_mul_f32_e32 v143, v143, v249
	v_cvt_pk_bf16_f32 v136, v136, v1
	v_cvt_pk_bf16_f32 v140, v140, v1
	v_cvt_pk_bf16_f32 v137, v137, v1
	v_cvt_pk_bf16_f32 v141, v141, v1
	v_cvt_pk_bf16_f32 v138, v138, v1
	v_cvt_pk_bf16_f32 v142, v142, v1
	v_cvt_pk_bf16_f32 v139, v139, v1
	v_cvt_pk_bf16_f32 v143, v143, v1
	ds_write_b16 v232, v136 offset:16400
	ds_write_b16 v232, v140 offset:16368
	ds_write_b16 v232, v137 offset:16928
	ds_write_b16 v232, v141 offset:16896
	ds_write_b16 v232, v138 offset:17456
	ds_write_b16 v232, v142 offset:17424
	ds_write_b16 v232, v139 offset:17984
	ds_write_b16 v232, v143 offset:17952
	v_mul_f32_e32 v128, v128, v250
	v_mul_f32_e32 v132, v132, v250
	v_mul_f32_e32 v129, v129, v251
	v_mul_f32_e32 v133, v133, v251
	v_mul_f32_e32 v130, v130, v252
	v_mul_f32_e32 v134, v134, v252
	v_mul_f32_e32 v131, v131, v253
	v_mul_f32_e32 v135, v135, v253
	v_cvt_pk_bf16_f32 v128, v128, v1
	v_cvt_pk_bf16_f32 v132, v132, v1
	v_cvt_pk_bf16_f32 v129, v129, v1
	v_cvt_pk_bf16_f32 v133, v133, v1
	v_cvt_pk_bf16_f32 v130, v130, v1
	v_cvt_pk_bf16_f32 v134, v134, v1
	v_cvt_pk_bf16_f32 v131, v131, v1
	v_cvt_pk_bf16_f32 v135, v135, v1
	ds_write_b16 v232, v128 offset:24848
	ds_write_b16 v232, v132 offset:24816
	ds_write_b16 v232, v129 offset:25376
	ds_write_b16 v232, v133 offset:25344
	ds_write_b16 v232, v130 offset:25904
	ds_write_b16 v232, v134 offset:25872
	ds_write_b16 v232, v131 offset:26432
	ds_write_b16 v232, v135 offset:26400
	s_waitcnt lgkmcnt(0)
	s_barrier
	s_and_saveexec_b64 vcc, s[28:29]
	s_cbranch_execz .LBB0_169
	s_waitcnt vmcnt(3)
	v_lshlrev_b32_e32 v140, 16, v124
	v_mul_f32_e32 v142, 0xbfb8aa3b, v140
	v_exp_f32_e32 v142, v142
	ds_read_b128 v[132:135], v233
	ds_read_b128 v[136:139], v213
	ds_read_b128 v[128:131], v213 offset:16
	s_waitcnt lgkmcnt(2)
	v_lshlrev_b32_e32 v141, 16, v132
	v_add_f32_e32 v142, 1.0, v142
	v_rcp_f32_e32 v142, v142
	s_waitcnt lgkmcnt(1)
	v_mov_b32_e32 v143, v136
	v_pk_mul_f32 v[140:141], v[142:143], v[140:141]
	s_nop 0
	v_mul_f32_e32 v142, v140, v141
	v_and_b32_e32 v140, 0xffff0000, v124
	v_mul_f32_e32 v124, 0xbfb8aa3b, v140
	v_exp_f32_e32 v124, v124
	v_and_b32_e32 v141, 0xffff0000, v132
	v_add_f32_e32 v124, 1.0, v124
	v_rcp_f32_e32 v136, v124
	s_nop 0
	v_pk_mul_f32 v[136:137], v[136:137], v[140:141]
	s_nop 0
	v_mul_f32_e32 v124, v136, v137
	v_lshlrev_b32_e32 v136, 16, v125
	v_mul_f32_e32 v132, 0xbfb8aa3b, v136
	v_exp_f32_e32 v132, v132
	v_mov_b32_e32 v141, v138
	v_lshlrev_b32_e32 v137, 16, v133
	v_and_b32_e32 v133, 0xffff0000, v133
	v_add_f32_e32 v132, 1.0, v132
	v_rcp_f32_e32 v140, v132
	v_and_b32_e32 v132, 0xffff0000, v125
	v_mul_f32_e32 v125, 0xbfb8aa3b, v132
	v_exp_f32_e32 v125, v125
	v_pk_mul_f32 v[136:137], v[140:141], v[136:137]
	v_cvt_pk_bf16_f32 v124, v142, v124
	v_add_f32_e32 v125, 1.0, v125
	v_rcp_f32_e32 v138, v125
	v_mul_f32_e32 v136, v136, v137
	s_waitcnt lgkmcnt(0)
	v_mov_b32_e32 v137, v128
	v_pk_mul_f32 v[132:133], v[138:139], v[132:133]
	s_nop 0
	v_mul_f32_e32 v125, v132, v133
	v_lshlrev_b32_e32 v132, 16, v126
	v_cvt_pk_bf16_f32 v125, v136, v125
	v_mul_f32_e32 v136, 0xbfb8aa3b, v132
	v_exp_f32_e32 v136, v136
	v_lshlrev_b32_e32 v133, 16, v134
	v_add_f32_e32 v136, 1.0, v136
	v_rcp_f32_e32 v136, v136
	s_nop 0
	v_pk_mul_f32 v[132:133], v[136:137], v[132:133]
	s_nop 0
	v_mul_f32_e32 v136, v132, v133
	v_and_b32_e32 v132, 0xffff0000, v126
	v_mul_f32_e32 v126, 0xbfb8aa3b, v132
	v_exp_f32_e32 v126, v126
	v_and_b32_e32 v133, 0xffff0000, v134
	v_add_f32_e32 v126, 1.0, v126
	v_rcp_f32_e32 v128, v126
	s_nop 0
	v_pk_mul_f32 v[128:129], v[128:129], v[132:133]
	s_nop 0
	v_mul_f32_e32 v126, v128, v129
	v_lshlrev_b32_e32 v128, 16, v127
	v_mul_f32_e32 v132, 0xbfb8aa3b, v128
	v_exp_f32_e32 v132, v132
	v_lshlrev_b32_e32 v129, 16, v135
	v_mov_b32_e32 v133, v130
	v_cvt_pk_bf16_f32 v126, v136, v126
	v_add_f32_e32 v132, 1.0, v132
	v_rcp_f32_e32 v132, v132
	s_nop 0
	v_pk_mul_f32 v[128:129], v[132:133], v[128:129]
	s_nop 0
	v_mul_f32_e32 v132, v128, v129
	v_and_b32_e32 v128, 0xffff0000, v127
	v_mul_f32_e32 v127, 0xbfb8aa3b, v128
	v_exp_f32_e32 v127, v127
	v_and_b32_e32 v129, 0xffff0000, v135
	v_add_f32_e32 v127, 1.0, v127
	v_rcp_f32_e32 v130, v127
	s_nop 0
	v_pk_mul_f32 v[128:129], v[130:131], v[128:129]
	s_nop 0
	v_mul_f32_e32 v127, v128, v129
	v_add_u32_e32 v128, s81, v216
	v_ashrrev_i32_e32 v129, 31, v128
	v_lshlrev_b64 v[128:129], 12, v[128:129]
	v_lshl_add_u64 v[128:129], v[184:185], 0, v[128:129]
	v_cvt_pk_bf16_f32 v127, v132, v127
	global_store_dwordx4 v[128:129], v[124:127], off
	s_or_b64 exec, exec, vcc
	s_and_saveexec_b64 vcc, s[30:31]
	s_cbranch_execnz .LBB0_170
